# grid barrier: the workgroup completing the top level bumps all XCD generation words itself; waiters poll their XCD word without a relay by their own leader
# speedup vs baseline: 1.0272x; 1.0002x over previous
; __device__ __forceinline__ unsigned xb_ld(unsigned* p)              { return __hip_atomic_load(p, __ATOMIC_RELAXED, __HIP_MEMORY_SCOPE_AGENT); }
; __device__ __forceinline__ unsigned xb_add(unsigned* p, unsigned v) { return __hip_atomic_fetch_add(p, v, __ATOMIC_RELAXED, __HIP_MEMORY_SCOPE_AGENT); }
; #define XB_SPIN(cond, bar) do { unsigned _sp = 0; while (cond) { __builtin_amdgcn_s_sleep(1); \
;     if ((++_sp & 255u) == 0u) { if (xb_ld(&(bar)[XB_TMO])) break; if (_sp > XB_SPIN_CAP) { atomicAdd(&(bar)[XB_TMO], 1u); break; } } } } while (0)
; __device__ __forceinline__ void xcd_barrier(const XcdBarrier& b) {
;     ...
;             const unsigned og = xb_add(&bar[XB_TOP], 1u);
;             const unsigned tg = og / nx;
;             if (og + 1u == (tg + 1u) * nx) xb_add(&bar[XB_TOPGEN], 1u);
;             else XB_SPIN(xb_ld(&bar[XB_TOPGEN]) == tg, bar);
;             __builtin_amdgcn_fence(__ATOMIC_ACQUIRE, "agent");
;             xb_add(&bar[XB_XGEN(b.x)], 1u);
.LBB0_83:
	s_or_b64 exec, exec, s[0:1]
	s_and_saveexec_b64 s[0:1], s[10:11]
	s_cbranch_execz .LBB0_85
	v_mov_b32_e32 v2, 1
	global_atomic_add v[0:1], v2, off
	s_add_u32 s98, s84, 0xc13500
	v_cmp_eq_u32_e32 vcc, s98, v0
	s_and_saveexec_b64 s[100:101], vcc
	v_mov_b32_e32 v3, 0xc12400
	global_atomic_add v3, v2, s[84:85]
	global_atomic_add v3, v2, s[84:85] offset:256
	global_atomic_add v3, v2, s[84:85] offset:512
	global_atomic_add v3, v2, s[84:85] offset:768
	global_atomic_add v3, v2, s[84:85] offset:1024
	global_atomic_add v3, v2, s[84:85] offset:1280
	global_atomic_add v3, v2, s[84:85] offset:1536
	global_atomic_add v3, v2, s[84:85] offset:1792
	global_atomic_add v3, v2, s[84:85] offset:2048
	global_atomic_add v3, v2, s[84:85] offset:2304
	global_atomic_add v3, v2, s[84:85] offset:2560
	global_atomic_add v3, v2, s[84:85] offset:2816
	global_atomic_add v3, v2, s[84:85] offset:3072
	global_atomic_add v3, v2, s[84:85] offset:3328
	global_atomic_add v3, v2, s[84:85] offset:3584
	global_atomic_add v3, v2, s[84:85] offset:3840
	s_mov_b64 exec, s[100:101]

; __device__ __forceinline__ unsigned xb_ld(unsigned* p)              { return __hip_atomic_load(p, __ATOMIC_RELAXED, __HIP_MEMORY_SCOPE_AGENT); }
; __device__ __forceinline__ unsigned xb_add(unsigned* p, unsigned v) { return __hip_atomic_fetch_add(p, v, __ATOMIC_RELAXED, __HIP_MEMORY_SCOPE_AGENT); }
; #define XB_SPIN(cond, bar) do { unsigned _sp = 0; while (cond) { __builtin_amdgcn_s_sleep(1); \
;     if ((++_sp & 255u) == 0u) { if (xb_ld(&(bar)[XB_TMO])) break; if (_sp > XB_SPIN_CAP) { atomicAdd(&(bar)[XB_TMO], 1u); break; } } } } while (0)
; __device__ __forceinline__ void xcd_barrier(const XcdBarrier& b) {
;     ...
;             const unsigned og = xb_add(&bar[XB_TOP], 1u);
;             const unsigned tg = og / nx;
;             if (og + 1u == (tg + 1u) * nx) xb_add(&bar[XB_TOPGEN], 1u);
;             else XB_SPIN(xb_ld(&bar[XB_TOPGEN]) == tg, bar);
;             __builtin_amdgcn_fence(__ATOMIC_ACQUIRE, "agent");
;             xb_add(&bar[XB_XGEN(b.x)], 1u);
.LBB0_523:
	s_or_b64 exec, exec, s[0:1]
	s_and_saveexec_b64 s[0:1], s[14:15]
	s_cbranch_execz .LBB0_525
	v_mov_b32_e32 v2, 1
	global_atomic_add v[0:1], v2, off
	s_add_u32 s98, s84, 0xc13500
	v_cmp_eq_u32_e32 vcc, s98, v0
	s_and_saveexec_b64 s[100:101], vcc
	v_mov_b32_e32 v3, 0xc12400
	global_atomic_add v3, v2, s[84:85]
	global_atomic_add v3, v2, s[84:85] offset:256
	global_atomic_add v3, v2, s[84:85] offset:512
	global_atomic_add v3, v2, s[84:85] offset:768
	global_atomic_add v3, v2, s[84:85] offset:1024
	global_atomic_add v3, v2, s[84:85] offset:1280
	global_atomic_add v3, v2, s[84:85] offset:1536
	global_atomic_add v3, v2, s[84:85] offset:1792
	global_atomic_add v3, v2, s[84:85] offset:2048
	global_atomic_add v3, v2, s[84:85] offset:2304
	global_atomic_add v3, v2, s[84:85] offset:2560
	global_atomic_add v3, v2, s[84:85] offset:2816
	global_atomic_add v3, v2, s[84:85] offset:3072
	global_atomic_add v3, v2, s[84:85] offset:3328
	global_atomic_add v3, v2, s[84:85] offset:3584
	global_atomic_add v3, v2, s[84:85] offset:3840
	s_mov_b64 exec, s[100:101]

; __device__ __forceinline__ unsigned xb_ld(unsigned* p)              { return __hip_atomic_load(p, __ATOMIC_RELAXED, __HIP_MEMORY_SCOPE_AGENT); }
; __device__ __forceinline__ unsigned xb_add(unsigned* p, unsigned v) { return __hip_atomic_fetch_add(p, v, __ATOMIC_RELAXED, __HIP_MEMORY_SCOPE_AGENT); }
; #define XB_SPIN(cond, bar) do { unsigned _sp = 0; while (cond) { __builtin_amdgcn_s_sleep(1); \
;     if ((++_sp & 255u) == 0u) { if (xb_ld(&(bar)[XB_TMO])) break; if (_sp > XB_SPIN_CAP) { atomicAdd(&(bar)[XB_TMO], 1u); break; } } } } while (0)
; __device__ __forceinline__ void xcd_barrier(const XcdBarrier& b) {
;     ...
;             const unsigned og = xb_add(&bar[XB_TOP], 1u);
;             const unsigned tg = og / nx;
;             if (og + 1u == (tg + 1u) * nx) xb_add(&bar[XB_TOPGEN], 1u);
;             else XB_SPIN(xb_ld(&bar[XB_TOPGEN]) == tg, bar);
;             __builtin_amdgcn_fence(__ATOMIC_ACQUIRE, "agent");
;             xb_add(&bar[XB_XGEN(b.x)], 1u);
.LBB0_853:
	s_or_b64 exec, exec, s[0:1]
	s_and_saveexec_b64 s[0:1], s[12:13]
	s_cbranch_execz .LBB0_855
	v_mov_b32_e32 v2, 1
	global_atomic_add v[0:1], v2, off
	s_add_u32 s98, s84, 0xc13500
	v_cmp_eq_u32_e32 vcc, s98, v0
	s_and_saveexec_b64 s[100:101], vcc
	v_mov_b32_e32 v3, 0xc12400
	global_atomic_add v3, v2, s[84:85]
	global_atomic_add v3, v2, s[84:85] offset:256
	global_atomic_add v3, v2, s[84:85] offset:512
	global_atomic_add v3, v2, s[84:85] offset:768
	global_atomic_add v3, v2, s[84:85] offset:1024
	global_atomic_add v3, v2, s[84:85] offset:1280
	global_atomic_add v3, v2, s[84:85] offset:1536
	global_atomic_add v3, v2, s[84:85] offset:1792
	global_atomic_add v3, v2, s[84:85] offset:2048
	global_atomic_add v3, v2, s[84:85] offset:2304
	global_atomic_add v3, v2, s[84:85] offset:2560
	global_atomic_add v3, v2, s[84:85] offset:2816
	global_atomic_add v3, v2, s[84:85] offset:3072
	global_atomic_add v3, v2, s[84:85] offset:3328
	global_atomic_add v3, v2, s[84:85] offset:3584
	global_atomic_add v3, v2, s[84:85] offset:3840
	s_mov_b64 exec, s[100:101]

; __device__ __forceinline__ unsigned xb_ld(unsigned* p)              { return __hip_atomic_load(p, __ATOMIC_RELAXED, __HIP_MEMORY_SCOPE_AGENT); }
; __device__ __forceinline__ unsigned xb_add(unsigned* p, unsigned v) { return __hip_atomic_fetch_add(p, v, __ATOMIC_RELAXED, __HIP_MEMORY_SCOPE_AGENT); }
; #define XB_SPIN(cond, bar) do { unsigned _sp = 0; while (cond) { __builtin_amdgcn_s_sleep(1); \
;     if ((++_sp & 255u) == 0u) { if (xb_ld(&(bar)[XB_TMO])) break; if (_sp > XB_SPIN_CAP) { atomicAdd(&(bar)[XB_TMO], 1u); break; } } } } while (0)
; __device__ __forceinline__ void xcd_barrier(const XcdBarrier& b) {
;     ...
;             const unsigned og = xb_add(&bar[XB_TOP], 1u);
;             const unsigned tg = og / nx;
;             if (og + 1u == (tg + 1u) * nx) xb_add(&bar[XB_TOPGEN], 1u);
;             else XB_SPIN(xb_ld(&bar[XB_TOPGEN]) == tg, bar);
;             __builtin_amdgcn_fence(__ATOMIC_ACQUIRE, "agent");
;             xb_add(&bar[XB_XGEN(b.x)], 1u);
.LBB0_1105:
	s_or_b64 exec, exec, s[0:1]
	s_and_saveexec_b64 s[0:1], s[18:19]
	s_cbranch_execz .LBB0_1107
	v_mov_b32_e32 v2, 1
	global_atomic_add v[0:1], v2, off
	s_add_u32 s98, s84, 0xc13500
	v_cmp_eq_u32_e32 vcc, s98, v0
	s_and_saveexec_b64 s[100:101], vcc
	v_mov_b32_e32 v3, 0xc12400
	global_atomic_add v3, v2, s[84:85]
	global_atomic_add v3, v2, s[84:85] offset:256
	global_atomic_add v3, v2, s[84:85] offset:512
	global_atomic_add v3, v2, s[84:85] offset:768
	global_atomic_add v3, v2, s[84:85] offset:1024
	global_atomic_add v3, v2, s[84:85] offset:1280
	global_atomic_add v3, v2, s[84:85] offset:1536
	global_atomic_add v3, v2, s[84:85] offset:1792
	global_atomic_add v3, v2, s[84:85] offset:2048
	global_atomic_add v3, v2, s[84:85] offset:2304
	global_atomic_add v3, v2, s[84:85] offset:2560
	global_atomic_add v3, v2, s[84:85] offset:2816
	global_atomic_add v3, v2, s[84:85] offset:3072
	global_atomic_add v3, v2, s[84:85] offset:3328
	global_atomic_add v3, v2, s[84:85] offset:3584
	global_atomic_add v3, v2, s[84:85] offset:3840
	s_mov_b64 exec, s[100:101]

; __device__ __forceinline__ unsigned xb_ld(unsigned* p)              { return __hip_atomic_load(p, __ATOMIC_RELAXED, __HIP_MEMORY_SCOPE_AGENT); }
; __device__ __forceinline__ unsigned xb_add(unsigned* p, unsigned v) { return __hip_atomic_fetch_add(p, v, __ATOMIC_RELAXED, __HIP_MEMORY_SCOPE_AGENT); }
; #define XB_SPIN(cond, bar) do { unsigned _sp = 0; while (cond) { __builtin_amdgcn_s_sleep(1); \
;     if ((++_sp & 255u) == 0u) { if (xb_ld(&(bar)[XB_TMO])) break; if (_sp > XB_SPIN_CAP) { atomicAdd(&(bar)[XB_TMO], 1u); break; } } } } while (0)
; __device__ __forceinline__ void xcd_barrier(const XcdBarrier& b) {
;     ...
;             const unsigned og = xb_add(&bar[XB_TOP], 1u);
;             const unsigned tg = og / nx;
;             if (og + 1u == (tg + 1u) * nx) xb_add(&bar[XB_TOPGEN], 1u);
;             else XB_SPIN(xb_ld(&bar[XB_TOPGEN]) == tg, bar);
;             __builtin_amdgcn_fence(__ATOMIC_ACQUIRE, "agent");
;             xb_add(&bar[XB_XGEN(b.x)], 1u);
.LBB0_1437:
	s_or_b64 exec, exec, s[4:5]
	s_and_saveexec_b64 s[4:5], s[10:11]
	s_cbranch_execz .LBB0_1439
	v_mov_b32_e32 v2, 1
	global_atomic_add v[0:1], v2, off
	s_add_u32 s98, s84, 0xc13500
	v_cmp_eq_u32_e32 vcc, s98, v0
	s_and_saveexec_b64 s[100:101], vcc
	v_mov_b32_e32 v3, 0xc12400
	global_atomic_add v3, v2, s[84:85]
	global_atomic_add v3, v2, s[84:85] offset:256
	global_atomic_add v3, v2, s[84:85] offset:512
	global_atomic_add v3, v2, s[84:85] offset:768
	global_atomic_add v3, v2, s[84:85] offset:1024
	global_atomic_add v3, v2, s[84:85] offset:1280
	global_atomic_add v3, v2, s[84:85] offset:1536
	global_atomic_add v3, v2, s[84:85] offset:1792
	global_atomic_add v3, v2, s[84:85] offset:2048
	global_atomic_add v3, v2, s[84:85] offset:2304
	global_atomic_add v3, v2, s[84:85] offset:2560
	global_atomic_add v3, v2, s[84:85] offset:2816
	global_atomic_add v3, v2, s[84:85] offset:3072
	global_atomic_add v3, v2, s[84:85] offset:3328
	global_atomic_add v3, v2, s[84:85] offset:3584
	global_atomic_add v3, v2, s[84:85] offset:3840
	s_mov_b64 exec, s[100:101]
